# sample S5 scans in the scan phase: the per-step operand loads of all four steps issued at the item start (cloned scalar address arithmetic)
# baseline (speedup 1.0000x reference)
.LBB0_1150:
	s_cmpk_gt_i32 s76, 0x3ff
	s_mov_b64 s[0:1], -1
	s_cbranch_scc0 .LBB0_1183
	s_lshr_b32 s28, s76, 1
	s_cmpk_gt_u32 s76, 0x7ff
	s_cbranch_scc0 .LBB0_1163
	s_cmpk_gt_u32 s76, 0xbff
	s_cbranch_scc0 .LBB0_1154
	s_and_b32 s5, s76, 31
	v_lshl_add_u32 v172, s5, 6, v64
	v_ashrrev_i32_e32 v173, 31, v172
	v_lshlrev_b64 v[174:175], 2, v[172:173]
	v_lshl_add_u64 v[170:171], s[80:81], 0, v[174:175]
	global_load_dword v177, v[170:171], off
	v_add_co_u32_e32 v170, vcc, 0x2000, v170
	s_add_i32 s0, s76, 0xfffff400
	s_nop 1
	v_addc_co_u32_e32 v171, vcc, 0, v171, vcc
	s_lshr_b32 s38, s0, 5
	global_load_dword v178, v[170:171], off
	s_lshl_b32 s4, s38, 2
	s_add_i32 s2, s4, 0x2040
	s_mul_i32 s6, s38, 0xc000
	s_add_i32 s7, s6, 0x60c0000
	s_mul_hi_u32 s8, s2, 0x3000
	s_add_u32 s7, s12, s7
	s_addc_u32 s9, s13, s8
	s_lshl_b32 s5, s5, 5
	s_add_u32 s8, s7, s5
	s_addc_u32 s9, s9, 0
	s_add_u32 s58, s8, 0x1ec00e00
	s_addc_u32 s59, s9, 0
	v_mov_b32_e32 v176, 0x1ec00000
	global_load_dwordx4 v[180:183], v176, s[8:9] offset:3584
	global_load_dwordx4 v[184:187], v97, s[58:59] offset:16
	s_add_i32 s38, s4, 0x2041
	s_add_i32 s2, s6, 0x60c3000
	s_mul_hi_u32 s3, s38, 0x3000
	s_add_u32 s2, s12, s2
	s_addc_u32 s3, s13, s3
	s_add_u32 s2, s2, s5
	s_addc_u32 s3, s3, 0
	s_add_u32 s8, s2, 0x1ec00e00
	s_addc_u32 s9, s3, 0
	global_load_dwordx4 v[188:191], v97, s[8:9] offset:16
	global_load_dwordx4 v[192:195], v176, s[2:3] offset:3584
	s_add_i32 s38, s4, 0x2042
	s_add_i32 s6, s6, 0x60c6000
	s_mul_hi_u32 s2, s38, 0x3000
	s_add_u32 s3, s12, s6
	s_addc_u32 s6, s13, s2
	s_add_u32 s2, s3, s5
	s_addc_u32 s3, s6, 0
	s_add_u32 s6, s2, 0x1ec00e00
	s_addc_u32 s7, s3, 0
	global_load_dwordx4 v[196:199], v97, s[6:7] offset:16
	global_load_dwordx4 v[200:203], v176, s[2:3] offset:3584
	s_add_i32 s38, s4, 0x2043
	s_mul_i32 s3, s38, 0x3000
	s_mul_hi_u32 s2, s38, 0x3000
	s_add_u32 s3, s12, s3
	s_addc_u32 s4, s13, s2
	s_add_u32 s2, s3, s5
	s_addc_u32 s3, s4, 0
	s_add_u32 s4, s2, 0x1ec00e00
	s_addc_u32 s5, s3, 0
	global_load_dwordx4 v[204:207], v97, s[4:5] offset:16
	global_load_dwordx4 v[208:211], v176, s[2:3] offset:3584
	s_and_b32 s5, s76, 31
	v_lshl_add_u32 v32, s5, 6, v64
	v_ashrrev_i32_e32 v33, 31, v32
	v_lshlrev_b64 v[36:37], 2, v[32:33]
	v_lshl_add_u64 v[0:1], s[80:81], 0, v[36:37]
	s_waitcnt vmcnt(0)
	v_mov_b32_e32 v38, v177
	v_add_co_u32_e32 v0, vcc, 0x2000, v0
	s_add_i32 s0, s76, 0xfffff400
	s_nop 0
	v_addc_co_u32_e32 v1, vcc, 0, v1, vcc
	s_lshr_b32 s38, s0, 5
	v_mov_b32_e32 v39, v178
	v_lshlrev_b32_e32 v0, 4, v32
	v_readlane_b32 s0, v255, 50
	v_ashrrev_i32_e32 v1, 31, v0
	v_readlane_b32 s1, v255, 51
	s_lshl_b32 s4, s38, 2
	s_add_i32 s2, s4, 0x2040
	v_lshl_add_u64 v[8:9], v[0:1], 2, s[0:1]
	s_mov_b64 s[0:1], 0x20000
	v_lshl_add_u64 v[24:25], v[8:9], 0, s[0:1]
	s_mov_b32 s0, 0x20000
	global_load_dwordx4 v[0:3], v[8:9], off offset:48
	global_load_dwordx4 v[4:7], v[8:9], off offset:32
	global_load_dwordx4 v[12:15], v[8:9], off offset:16
	global_load_dwordx4 v[20:23], v[8:9], off
	v_add_co_u32_e32 v8, vcc, s0, v8
	s_lshl_b64 s[0:1], s[38:39], 11
	s_mul_i32 s6, s38, 0xc000
	s_add_u32 s0, s0, s14
	s_addc_u32 s1, s1, s15
	s_add_i32 s7, s6, 0x60c0000
	v_readlane_b32 s52, v255, 6
	s_mul_hi_u32 s8, s2, 0x3000
	s_add_u32 s7, s12, s7
	v_readlane_b32 s53, v255, 7
	v_readlane_b32 s54, v255, 8
	v_readlane_b32 s55, v255, 9
	v_readlane_b32 s56, v255, 10
	v_readlane_b32 s57, v255, 11
	v_readlane_b32 s58, v255, 12
	v_readlane_b32 s59, v255, 13
	v_readlane_b32 s60, v255, 14
	v_readlane_b32 s61, v255, 15
	v_readlane_b32 s62, v255, 16
	v_readlane_b32 s63, v255, 17
	s_addc_u32 s9, s13, s8
	s_lshl_b32 s5, s5, 5
	v_lshl_add_u64 v[32:33], s[0:1], 0, v[32:33]
	v_readlane_b32 s64, v255, 18
	v_readlane_b32 s65, v255, 19
	v_readlane_b32 s66, v255, 20
	v_readlane_b32 s67, v255, 21
	s_mov_b64 s[52:53], s[56:57]
	s_add_u32 s8, s7, s5
	v_lshlrev_b64 v[32:33], 2, v[32:33]
	s_mov_b64 s[54:55], s[58:59]
	s_mov_b64 s[56:57], s[60:61]
	s_mov_b64 s[58:59], s[62:63]
	s_addc_u32 s9, s9, 0
	s_mov_b64 s[60:61], s[64:65]
	s_mov_b64 s[62:63], s[66:67]
	v_lshl_add_u64 v[34:35], s[58:59], 0, v[32:33]
	s_add_u32 s58, s8, 0x1ec00e00
	v_addc_co_u32_e32 v9, vcc, 0, v9, vcc
	v_lshl_add_u64 v[32:33], s[56:57], 0, v[32:33]
	s_addc_u32 s59, s9, 0
	v_mov_b32_e32 v56, 0x1ec00000
	global_load_dwordx4 v[28:31], v[8:9], off
	s_nop 0
	global_load_dwordx4 v[8:11], v[24:25], off offset:48
	global_load_dwordx4 v[16:19], v[24:25], off offset:32
	s_nop 0
	global_load_dwordx4 v[24:27], v[24:25], off offset:16
	s_mov_b32 s3, s39
	global_load_dword v44, v[34:35], off
	global_load_dword v45, v[32:33], off
	v_mov_b64_e32 v[40:41], v[180:181]
	v_mov_b64_e32 v[42:43], v[182:183]
	s_lshl_b64 s[2:3], s[2:3], 13
	v_mov_b64_e32 v[32:33], v[184:185]
	v_mov_b64_e32 v[34:35], v[186:187]
	s_add_u32 s2, s89, s2
	s_addc_u32 s3, s90, s3
	s_add_i32 s38, s4, 0x2041
	s_mov_b32 s33, 0x4480000
	s_movk_i32 s53, 0x6000
	s_movk_i32 s52, 0x4000
	s_waitcnt vmcnt(0)
	v_lshlrev_b32_e32 v46, 16, v40
	v_and_b32_e32 v40, 0xffff0000, v40
	v_fma_f32 v54, v20, v46, 0
	v_fma_f32 v46, v28, v46, 0
	v_lshlrev_b32_e32 v47, 16, v41
	v_fmac_f32_e32 v54, v21, v40
	v_fmac_f32_e32 v46, v29, v40
	v_and_b32_e32 v41, 0xffff0000, v41
	v_fmac_f32_e32 v54, v22, v47
	v_fmac_f32_e32 v46, v30, v47
	v_lshlrev_b32_e32 v48, 16, v42
	v_fmac_f32_e32 v54, v23, v41
	v_fmac_f32_e32 v46, v31, v41
	v_and_b32_e32 v42, 0xffff0000, v42
	v_fmac_f32_e32 v54, v12, v48
	v_fmac_f32_e32 v46, v24, v48
	v_lshlrev_b32_e32 v49, 16, v43
	v_fmac_f32_e32 v54, v13, v42
	v_fmac_f32_e32 v46, v25, v42
	v_and_b32_e32 v43, 0xffff0000, v43
	v_fmac_f32_e32 v54, v14, v49
	v_fmac_f32_e32 v46, v26, v49
	v_lshlrev_b32_e32 v50, 16, v32
	v_fmac_f32_e32 v54, v15, v43
	v_fmac_f32_e32 v46, v27, v43
	v_and_b32_e32 v32, 0xffff0000, v32
	v_fmac_f32_e32 v54, v4, v50
	v_fmac_f32_e32 v46, v16, v50
	v_lshlrev_b32_e32 v51, 16, v33
	v_fmac_f32_e32 v54, v5, v32
	v_fmac_f32_e32 v46, v17, v32
	v_and_b32_e32 v33, 0xffff0000, v33
	v_fmac_f32_e32 v54, v6, v51
	v_fmac_f32_e32 v46, v18, v51
	v_lshlrev_b32_e32 v52, 16, v34
	v_fmac_f32_e32 v54, v7, v33
	v_fmac_f32_e32 v46, v19, v33
	v_and_b32_e32 v34, 0xffff0000, v34
	v_fmac_f32_e32 v54, v0, v52
	v_fmac_f32_e32 v46, v8, v52
	v_lshlrev_b32_e32 v53, 16, v35
	v_fmac_f32_e32 v54, v1, v34
	v_fmac_f32_e32 v46, v9, v34
	v_and_b32_e32 v35, 0xffff0000, v35
	v_fmac_f32_e32 v54, v2, v53
	v_fmac_f32_e32 v46, v10, v53
	v_fmac_f32_e32 v54, v3, v35
	v_fmac_f32_e32 v46, v11, v35
	v_lshl_add_u64 v[34:35], s[2:3], 0, v[36:37]
	s_add_i32 s2, s6, 0x60c3000
	v_mul_f32_e32 v32, v39, v44
	s_mul_hi_u32 s3, s38, 0x3000
	s_add_u32 s2, s12, s2
	v_fma_f32 v32, v38, v45, -v32
	s_addc_u32 s3, s13, s3
	v_add_f32_e32 v32, v32, v54
	v_mul_f32_e32 v33, v39, v45
	s_add_u32 s2, s2, s5
	v_fmac_f32_e32 v33, v38, v44
	global_store_dword v[34:35], v32, off
	v_add_co_u32_e32 v34, vcc, s33, v34
	s_addc_u32 s3, s3, 0
	v_add_f32_e32 v33, v33, v46
	v_addc_co_u32_e32 v35, vcc, 0, v35, vcc
	s_add_u32 s8, s2, 0x1ec00e00
	global_store_dword v[34:35], v33, off
	s_addc_u32 s9, s3, 0
	v_mov_b64_e32 v[40:41], v[188:189]
	v_mov_b64_e32 v[42:43], v[190:191]
	v_mov_b64_e32 v[44:45], v[192:193]
	v_mov_b64_e32 v[46:47], v[194:195]
	s_lshl_b64 s[2:3], s[38:39], 13
	s_add_u32 s2, s89, s2
	s_addc_u32 s3, s90, s3
	s_add_i32 s38, s4, 0x2042
	s_add_i32 s6, s6, 0x60c6000
	s_waitcnt vmcnt(0)
	v_lshlrev_b32_e32 v50, 16, v40
	s_waitcnt vmcnt(0)
	v_lshlrev_b32_e32 v34, 16, v44
	v_and_b32_e32 v35, 0xffff0000, v44
	v_fma_f32 v54, v20, v34, 0
	v_fma_f32 v34, v28, v34, 0
	v_lshlrev_b32_e32 v44, 16, v45
	v_fmac_f32_e32 v34, v29, v35
	v_and_b32_e32 v45, 0xffff0000, v45
	v_fmac_f32_e32 v34, v30, v44
	v_lshlrev_b32_e32 v48, 16, v46
	v_fmac_f32_e32 v54, v21, v35
	v_fmac_f32_e32 v34, v31, v45
	v_and_b32_e32 v46, 0xffff0000, v46
	v_fmac_f32_e32 v54, v22, v44
	v_fmac_f32_e32 v34, v24, v48
	v_lshlrev_b32_e32 v49, 16, v47
	v_fmac_f32_e32 v54, v23, v45
	v_fmac_f32_e32 v34, v25, v46
	v_and_b32_e32 v47, 0xffff0000, v47
	v_fmac_f32_e32 v54, v12, v48
	v_fmac_f32_e32 v34, v26, v49
	v_fmac_f32_e32 v54, v13, v46
	v_fmac_f32_e32 v34, v27, v47
	v_and_b32_e32 v40, 0xffff0000, v40
	v_fmac_f32_e32 v54, v14, v49
	v_fmac_f32_e32 v34, v16, v50
	v_lshlrev_b32_e32 v51, 16, v41
	v_fmac_f32_e32 v54, v15, v47
	v_fmac_f32_e32 v34, v17, v40
	v_and_b32_e32 v41, 0xffff0000, v41
	v_fmac_f32_e32 v54, v4, v50
	v_fmac_f32_e32 v34, v18, v51
	v_lshlrev_b32_e32 v52, 16, v42
	v_fmac_f32_e32 v54, v5, v40
	v_fmac_f32_e32 v34, v19, v41
	v_and_b32_e32 v42, 0xffff0000, v42
	v_fmac_f32_e32 v54, v6, v51
	v_fmac_f32_e32 v34, v8, v52
	v_lshlrev_b32_e32 v53, 16, v43
	v_fmac_f32_e32 v54, v7, v41
	v_fmac_f32_e32 v34, v9, v42
	v_mul_f32_e32 v35, v39, v33
	v_and_b32_e32 v43, 0xffff0000, v43
	v_fmac_f32_e32 v54, v0, v52
	v_fmac_f32_e32 v34, v10, v53
	v_fma_f32 v35, v38, v32, -v35
	v_mul_f32_e32 v32, v39, v32
	v_fmac_f32_e32 v54, v1, v42
	v_fmac_f32_e32 v34, v11, v43
	v_fmac_f32_e32 v32, v38, v33
	v_fmac_f32_e32 v54, v2, v53
	v_add_f32_e32 v42, v32, v34
	v_lshl_add_u64 v[32:33], s[2:3], 0, v[36:37]
	s_mul_hi_u32 s2, s38, 0x3000
	s_add_u32 s3, s12, s6
	v_fmac_f32_e32 v54, v3, v43
	s_addc_u32 s6, s13, s2
	v_add_f32_e32 v40, v35, v54
	s_add_u32 s2, s3, s5
	global_store_dword v[32:33], v40, off
	v_add_co_u32_e32 v32, vcc, s33, v32
	s_addc_u32 s3, s6, 0
	s_nop 0
	v_addc_co_u32_e32 v33, vcc, 0, v33, vcc
	s_add_u32 s6, s2, 0x1ec00e00
	global_store_dword v[32:33], v42, off
	s_addc_u32 s7, s3, 0
	v_mov_b64_e32 v[32:33], v[196:197]
	v_mov_b64_e32 v[34:35], v[198:199]
	v_mov_b64_e32 v[44:45], v[200:201]
	v_mov_b64_e32 v[46:47], v[202:203]
	s_lshl_b64 s[2:3], s[38:39], 13
	s_add_u32 s2, s89, s2
	s_addc_u32 s3, s90, s3
	s_add_i32 s38, s4, 0x2043
	s_waitcnt vmcnt(0)
	v_lshlrev_b32_e32 v50, 16, v32
	s_waitcnt vmcnt(0)
	v_lshlrev_b32_e32 v41, 16, v44
	v_and_b32_e32 v43, 0xffff0000, v44
	v_fma_f32 v54, v20, v41, 0
	v_lshlrev_b32_e32 v44, 16, v45
	v_fmac_f32_e32 v54, v21, v43
	v_and_b32_e32 v45, 0xffff0000, v45
	v_fma_f32 v55, v28, v41, 0
	v_fmac_f32_e32 v54, v22, v44
	v_lshlrev_b32_e32 v48, 16, v46
	v_fmac_f32_e32 v55, v29, v43
	v_fmac_f32_e32 v54, v23, v45
	v_and_b32_e32 v46, 0xffff0000, v46
	v_fmac_f32_e32 v55, v30, v44
	v_fmac_f32_e32 v54, v12, v48
	v_lshlrev_b32_e32 v49, 16, v47
	v_fmac_f32_e32 v55, v31, v45
	v_fmac_f32_e32 v54, v13, v46
	v_and_b32_e32 v47, 0xffff0000, v47
	v_fmac_f32_e32 v55, v24, v48
	v_fmac_f32_e32 v54, v14, v49
	v_fmac_f32_e32 v55, v25, v46
	v_fmac_f32_e32 v54, v15, v47
	v_and_b32_e32 v32, 0xffff0000, v32
	v_fmac_f32_e32 v55, v26, v49
	v_fmac_f32_e32 v54, v4, v50
	v_lshlrev_b32_e32 v51, 16, v33
	v_fmac_f32_e32 v55, v27, v47
	v_fmac_f32_e32 v54, v5, v32
	v_and_b32_e32 v33, 0xffff0000, v33
	v_fmac_f32_e32 v55, v16, v50
	v_fmac_f32_e32 v54, v6, v51
	v_lshlrev_b32_e32 v52, 16, v34
	v_fmac_f32_e32 v55, v17, v32
	v_fmac_f32_e32 v54, v7, v33
	v_and_b32_e32 v34, 0xffff0000, v34
	v_fmac_f32_e32 v55, v18, v51
	v_fmac_f32_e32 v54, v0, v52
	v_lshlrev_b32_e32 v53, 16, v35
	v_fmac_f32_e32 v55, v19, v33
	v_fmac_f32_e32 v54, v1, v34
	v_and_b32_e32 v35, 0xffff0000, v35
	v_fmac_f32_e32 v55, v8, v52
	v_fmac_f32_e32 v54, v2, v53
	v_mul_f32_e32 v32, v39, v42
	v_fmac_f32_e32 v55, v9, v34
	v_fmac_f32_e32 v54, v3, v35
	v_fma_f32 v32, v38, v40, -v32
	v_fmac_f32_e32 v55, v10, v53
	v_add_f32_e32 v41, v32, v54
	v_mul_f32_e32 v32, v39, v40
	v_fmac_f32_e32 v55, v11, v35
	v_fmac_f32_e32 v32, v38, v42
	v_add_f32_e32 v40, v32, v55
	v_lshl_add_u64 v[32:33], s[2:3], 0, v[36:37]
	s_mul_i32 s3, s38, 0x3000
	s_mul_hi_u32 s2, s38, 0x3000
	s_add_u32 s3, s12, s3
	s_addc_u32 s4, s13, s2
	s_add_u32 s2, s3, s5
	global_store_dword v[32:33], v41, off
	v_add_co_u32_e32 v32, vcc, s33, v32
	s_addc_u32 s3, s4, 0
	s_nop 0
	v_addc_co_u32_e32 v33, vcc, 0, v33, vcc
	s_add_u32 s4, s2, 0x1ec00e00
	global_store_dword v[32:33], v40, off
	s_addc_u32 s5, s3, 0
	v_mov_b64_e32 v[32:33], v[204:205]
	v_mov_b64_e32 v[34:35], v[206:207]
	v_mov_b64_e32 v[42:43], v[208:209]
	v_mov_b64_e32 v[44:45], v[210:211]
	s_lshl_b64 s[2:3], s[38:39], 13
	s_add_u32 s2, s89, s2
	s_addc_u32 s3, s90, s3
	s_lshl_b64 s[0:1], s[0:1], 2
	s_add_u32 s0, s10, s0
	s_addc_u32 s1, s11, s1
	s_waitcnt vmcnt(0)
	v_lshlrev_b32_e32 v50, 16, v32
	s_waitcnt vmcnt(0)
	v_lshlrev_b32_e32 v46, 16, v42
	v_and_b32_e32 v42, 0xffff0000, v42
	v_fma_f32 v20, v20, v46, 0
	v_lshlrev_b32_e32 v47, 16, v43
	v_fmac_f32_e32 v20, v21, v42
	v_and_b32_e32 v43, 0xffff0000, v43
	v_fma_f32 v28, v28, v46, 0
	v_fmac_f32_e32 v20, v22, v47
	v_lshlrev_b32_e32 v48, 16, v44
	v_fmac_f32_e32 v28, v29, v42
	v_fmac_f32_e32 v20, v23, v43
	v_and_b32_e32 v44, 0xffff0000, v44
	v_fmac_f32_e32 v28, v30, v47
	v_fmac_f32_e32 v20, v12, v48
	v_lshlrev_b32_e32 v49, 16, v45
	v_fmac_f32_e32 v28, v31, v43
	v_fmac_f32_e32 v20, v13, v44
	v_and_b32_e32 v45, 0xffff0000, v45
	v_fmac_f32_e32 v28, v24, v48
	v_fmac_f32_e32 v20, v14, v49
	v_fmac_f32_e32 v28, v25, v44
	v_fmac_f32_e32 v20, v15, v45
	v_and_b32_e32 v32, 0xffff0000, v32
	v_fmac_f32_e32 v28, v26, v49
	v_fmac_f32_e32 v20, v4, v50
	v_lshlrev_b32_e32 v51, 16, v33
	v_fmac_f32_e32 v28, v27, v45
	v_fmac_f32_e32 v20, v5, v32
	v_and_b32_e32 v33, 0xffff0000, v33
	v_fmac_f32_e32 v28, v16, v50
	v_fmac_f32_e32 v20, v6, v51
	v_lshlrev_b32_e32 v52, 16, v34
	v_fmac_f32_e32 v28, v17, v32
	v_fmac_f32_e32 v20, v7, v33
	v_and_b32_e32 v34, 0xffff0000, v34
	v_fmac_f32_e32 v28, v18, v51
	v_fmac_f32_e32 v20, v0, v52
	v_lshlrev_b32_e32 v53, 16, v35
	v_fmac_f32_e32 v28, v19, v33
	v_fmac_f32_e32 v20, v1, v34
	v_and_b32_e32 v35, 0xffff0000, v35
	v_fmac_f32_e32 v28, v8, v52
	v_fmac_f32_e32 v20, v2, v53
	v_mul_f32_e32 v0, v39, v40
	v_fmac_f32_e32 v28, v9, v34
	v_fmac_f32_e32 v20, v3, v35
	v_fma_f32 v0, v38, v41, -v0
	v_fmac_f32_e32 v28, v10, v53
	v_add_f32_e32 v1, v0, v20
	v_mul_f32_e32 v0, v39, v41
	v_lshl_add_u64 v[2:3], s[2:3], 0, v[36:37]
	v_fmac_f32_e32 v28, v11, v35
	v_fmac_f32_e32 v0, v38, v40
	global_store_dword v[2:3], v1, off
	v_add_co_u32_e32 v2, vcc, s33, v2
	v_add_f32_e32 v0, v0, v28
	s_nop 0
	v_addc_co_u32_e32 v3, vcc, 0, v3, vcc
	global_store_dword v[2:3], v0, off
	v_lshl_add_u64 v[2:3], s[0:1], 0, v[36:37]
	v_add_co_u32_e32 v4, vcc, 0x89bc000, v2
	s_mov_b64 s[0:1], 0
	s_nop 0
	v_addc_co_u32_e32 v5, vcc, 0, v3, vcc
	v_add_co_u32_e32 v2, vcc, 0x8ddc000, v2
	global_store_dword v[4:5], v1, off
	s_nop 0
	v_addc_co_u32_e32 v3, vcc, 0, v3, vcc
	global_store_dword v[2:3], v0, off
